# FFN2-down (layer 0): same slice-first unit order as FFN1-down
# baseline (speedup 1.0000x reference)
.LBB0_1550:
	s_cmp_gt_u32 s76, 256
	s_cbranch_scc1 .Lrm2_p_done
	s_cmp_lg_u32 s10, 432
	s_cbranch_scc1 .Lrm2_p_done
	s_cmp_lt_u32 s75, 176
	s_cbranch_scc0 .Lrm2_p_done
	s_mul_hi_u32 s84, s75, 0xba2e8ba3
	s_lshr_b32 s84, s84, 3
	s_mul_i32 s85, s84, 11
	s_sub_u32 s85, s75, s85
	s_lshr_b32 s67, s84, 2
	s_add_u32 s67, s67, 64
	s_and_b32 s68, s84, 3
	s_lshl_b32 s6, s85, 2
	s_mov_b32 s69, 4

.LBB0_1556:
	s_add_i32 s63, s63, 1
	v_readlane_b32 s4, v253, 10
	s_mul_i32 s4, s63, s4
	s_mul_hi_u32 s5, s63, s76
	s_add_i32 s5, s5, s4
	s_mul_i32 s4, s63, s76
	s_add_u32 s8, s4, s75
	v_readlane_b32 s4, v253, 9
	s_addc_u32 s9, s5, s4
	s_cmp_gt_u32 s76, 256
	s_cbranch_scc1 .Lrm2_done
	s_cmp_lg_u32 s10, 432
	s_cbranch_scc1 .Lrm2_done
	s_cmp_lg_u32 s9, 0
	s_cbranch_scc1 .Lrm2_done
	s_cmp_ge_u32 s8, 432
	s_cbranch_scc1 .Lrm2_done
	s_cmp_lt_u32 s8, 176
	s_cbranch_scc1 .Lrm2_add
	s_cmp_lt_u32 s8, 256
	s_cbranch_scc1 .Lrm2_done
	s_sub_u32 s8, s8, 256
	s_branch .Lrm2_done

.Lrm2_done:
	s_waitcnt lgkmcnt(0)
	v_mov_b64_e32 v[2:3], s[10:11]
	v_cmp_ge_i64_e32 vcc, s[8:9], v[2:3]
	v_cmp_lt_i64_e64 s[4:5], s[8:9], v[2:3]
	s_cbranch_vccnz .LBB0_1565
	v_cmp_lt_i64_e32 vcc, s[8:9], v[146:147]
	s_mov_b64 s[24:25], -1
	s_cbranch_vccnz .LBB0_1559
	s_add_i32 s7, s8, 0xffffff00
	s_mul_hi_i32 s9, s7, 0x2e8ba2e9
	s_ashr_i32 s22, s9, 1
	s_lshr_b32 s23, s9, 31
	s_ashr_i32 s9, s9, 3
	s_add_i32 s22, s22, s23
	s_add_i32 s9, s9, s23
	s_add_i32 s64, s9, 64
	s_ashr_i32 s9, s22, 31
	s_lshr_b32 s9, s9, 30
	s_mul_i32 s24, s22, 11
	s_add_i32 s9, s22, s9
	s_sub_i32 s7, s7, s24
	s_and_b32 s9, s9, -4
	s_sub_i32 s65, s22, s9
	s_lshl_b32 s22, s7, 2
	s_mov_b64 s[24:25], 0
